# attention Q blocks loaded as full 128-byte lines (nt, read once), staged through the idle LDS ring into the MFMA fragment layout; first-tile wait no longer drains the tile DMAs
# speedup vs baseline: 1.0071x; 1.0071x over previous
.LBB0_534:
	s_mov_b32 s98, 0x9700000
	s_and_b64 s[100:101], s[8:9], exec
	s_cselect_b32 s98, s64, s98
	s_add_u32 s98, s26, s98
	s_addc_u32 s99, s27, 0
	s_lshl_b32 s100, s24, 10
	s_add_u32 s98, s98, s100
	s_addc_u32 s99, s99, 0
	s_lshl_b32 s100, s25, 7
	s_add_u32 s98, s98, s100
	s_addc_u32 s99, s99, 0
	v_lshrrev_b32_e32 v244, 3, v186
	v_and_b32_e32 v245, 7, v186
	v_lshlrev_b32_e32 v246, 10, v244
	v_lshl_or_b32 v246, v245, 4, v246
	v_mov_b32_e32 v247, 0
	v_lshl_add_u64 v[246:247], s[98:99], 0, v[246:247]
	s_mov_b64 s[100:101], 0x2000
	global_load_dwordx4 v[212:215], v[246:247], off nt
	v_lshl_add_u64 v[246:247], v[246:247], 0, s[100:101]
	global_load_dwordx4 v[216:219], v[246:247], off nt
	v_lshl_add_u64 v[246:247], v[246:247], 0, s[100:101]
	global_load_dwordx4 v[220:223], v[246:247], off nt
	v_lshl_add_u64 v[246:247], v[246:247], 0, s[100:101]
	global_load_dwordx4 v[224:227], v[246:247], off nt
	s_and_b64 s[100:101], s[14:15], exec
	s_movk_i32 s100, 0x2000
	s_cselect_b32 s100, 0xffffa000, s100
	s_ashr_i32 s101, s100, 31
	v_lshl_add_u64 v[246:247], v[246:247], 0, s[100:101]
	s_mov_b64 s[100:101], 0x2000
	global_load_dwordx4 v[228:231], v[246:247], off nt
	v_lshl_add_u64 v[246:247], v[246:247], 0, s[100:101]
	global_load_dwordx4 v[232:235], v[246:247], off nt
	v_lshl_add_u64 v[246:247], v[246:247], 0, s[100:101]
	global_load_dwordx4 v[236:239], v[246:247], off nt
	v_lshl_add_u64 v[246:247], v[246:247], 0, s[100:101]
	global_load_dwordx4 v[240:243], v[246:247], off nt
	v_mul_u32_u24_e32 v248, 0x90, v244
	v_lshl_add_u32 v248, v245, 4, v248
	v_add_u32_e32 v248, s63, v248
	v_and_b32_e32 v249, 31, v186
	v_lshrrev_b32_e32 v244, 5, v186
	v_mul_u32_u24_e32 v249, 0x90, v249
	v_lshl_add_u32 v249, v244, 4, v249
	v_add_u32_e32 v249, s63, v249
	s_waitcnt vmcnt(0)
	ds_write_b128 v248, v[212:215]
	ds_write_b128 v248, v[216:219] offset:1152
	ds_write_b128 v248, v[220:223] offset:2304
	ds_write_b128 v248, v[224:227] offset:3456
	ds_write_b128 v248, v[228:231] offset:4608
	ds_write_b128 v248, v[232:235] offset:5760
	ds_write_b128 v248, v[236:239] offset:6912
	ds_write_b128 v248, v[240:243] offset:8064
	s_waitcnt lgkmcnt(0)
	ds_read_b128 v[212:215], v249
	ds_read_b128 v[216:219], v249 offset:32
	ds_read_b128 v[220:223], v249 offset:64
	ds_read_b128 v[224:227], v249 offset:96
	ds_read_b128 v[228:231], v249 offset:4608
	ds_read_b128 v[232:235], v249 offset:4640
	ds_read_b128 v[236:239], v249 offset:4672
	ds_read_b128 v[240:243], v249 offset:4704
	s_waitcnt lgkmcnt(0)
	s_sub_i32 s73, s41, s69
	s_abs_i32 s37, s73
	v_cvt_f32_u32_e32 v2, s37
	s_sub_i32 s38, 0, s37
	v_lshlrev_b32_e32 v16, 4, v186
	v_ashrrev_i32_e32 v17, 31, v16
	v_rcp_iflag_f32_e32 v2, v2
	v_readfirstlane_b32 s44, v1
	v_mul_f32_e32 v2, 0x4f7ffffe, v2
	v_cvt_u32_f32_e32 v2, v2
	s_nop 0
	v_readfirstlane_b32 s39, v2
	s_mul_i32 s38, s38, s39
	s_mul_hi_u32 s38, s39, s38
	s_add_i32 s39, s39, s38
	s_mul_hi_u32 s38, s69, s39
	s_mul_i32 s38, s38, s37
	s_sub_i32 s38, s69, s38
	s_sub_i32 s40, s38, s37
	s_cmp_ge_u32 s38, s37
	s_cselect_b32 s38, s40, s38
	s_sub_i32 s40, s38, s37
	s_cmp_ge_u32 s38, s37
	s_cselect_b32 s38, s40, s38
	s_sub_i32 s38, s73, s38
	s_ashr_i32 s40, s38, 31
	s_abs_i32 s38, s38
	s_mul_hi_u32 s39, s38, s39
	s_mul_i32 s39, s39, s37
	s_sub_i32 s38, s38, s39
	s_sub_i32 s39, s38, s37
	s_cmp_ge_u32 s38, s37
	s_cselect_b32 s38, s39, s38
	s_sub_i32 s39, s38, s37
	s_cmp_ge_u32 s38, s37
	s_cselect_b32 s37, s39, s38
	s_xor_b32 s37, s37, s40
	s_sub_i32 s37, s37, s40
	s_add_i32 s38, s37, 1
	s_cmp_lg_u32 s38, s73
	s_cselect_b32 s78, s38, 0
	s_add_i32 s38, s37, s69
	s_ashr_i32 s39, s38, 31
	s_lshl_b64 s[40:41], s[38:39], 12
	s_add_u32 s42, s30, s40
	s_addc_u32 s43, s31, s41
	v_lshl_add_u64 v[4:5], s[42:43], 0, v[16:17]
	s_add_u32 s40, s58, s40
	s_mov_b32 s37, m0
	s_mov_b32 m0, s44
	s_nop 0
	global_load_lds_dwordx4 v[4:5], off
	global_load_lds_dwordx4 v[4:5], off offset:1024
	global_load_lds_dwordx4 v[4:5], off offset:2048
	global_load_lds_dwordx4 v[4:5], off offset:3072
	s_mov_b32 m0, s37
	s_addc_u32 s41, s59, s41
	s_add_i32 s37, s44, 0x1000
	s_cmp_gt_i32 s73, 1
	v_lshl_add_u64 v[4:5], s[40:41], 0, v[16:17]
	s_mov_b32 s39, m0
	s_mov_b32 m0, s37
	s_nop 0
	global_load_lds_dwordx4 v[4:5], off
	global_load_lds_dwordx4 v[4:5], off offset:1024
	global_load_lds_dwordx4 v[4:5], off offset:2048
	global_load_lds_dwordx4 v[4:5], off offset:3072
	s_mov_b32 m0, s39
	s_cselect_b64 s[60:61], -1, 0
	s_cmp_lt_i32 s73, 2
	s_cselect_b64 s[40:41], -1, 0
	s_and_b64 vcc, exec, s[40:41]
	s_cbranch_vccnz .LBB0_536
	s_add_i32 s42, s78, s69
	s_ashr_i32 s43, s42, 31
	s_lshl_b64 s[42:43], s[42:43], 12
	s_add_u32 s44, s30, s42
	s_addc_u32 s45, s31, s43
	s_add_u32 s42, s58, s42
	s_addc_u32 s43, s59, s43
	v_readfirstlane_b32 s37, v1
	v_lshl_add_u64 v[4:5], s[44:45], 0, v[16:17]
	v_lshl_add_u64 v[6:7], s[42:43], 0, v[16:17]
	s_add_i32 s39, s37, 0x2000
	s_mov_b32 s42, m0
	s_mov_b32 m0, s39
	s_nop 0
	global_load_lds_dwordx4 v[4:5], off
	global_load_lds_dwordx4 v[4:5], off offset:1024
	global_load_lds_dwordx4 v[4:5], off offset:2048
	global_load_lds_dwordx4 v[4:5], off offset:3072
	s_mov_b32 m0, s42
	s_addk_i32 s37, 0x3000
	s_mov_b32 s39, m0
	s_mov_b32 m0, s37
	s_nop 0
	global_load_lds_dwordx4 v[6:7], off
	global_load_lds_dwordx4 v[6:7], off offset:1024
	global_load_lds_dwordx4 v[6:7], off offset:2048
	global_load_lds_dwordx4 v[6:7], off offset:3072
	s_mov_b32 m0, s39
.LBB0_536:
	s_lshl_b32 s68, s25, 6
	s_cmp_lt_i32 s73, 1
	v_and_b32_e32 v188, 31, v186
	s_cbranch_scc1 .LBB0_549
	s_and_b64 s[42:43], s[8:9], exec
	s_cselect_b32 s37, s64, 0x9700000
	v_add_u32_e32 v2, s24, v188
	s_waitcnt lgkmcnt(0)
	s_add_u32 s42, s26, s37
	v_ashrrev_i32_e32 v19, 5, v186
	s_addc_u32 s43, s27, 0
	v_lshlrev_b64 v[4:5], 10, v[2:3]
	v_lshl_add_u64 v[4:5], s[42:43], 0, v[4:5]
	s_lshl_b32 s42, s68, 1
	s_mov_b32 s43, s36
	v_lshlrev_b32_e32 v6, 3, v19
	v_lshl_add_u64 v[4:5], v[4:5], 0, s[42:43]
	v_ashrrev_i32_e32 v7, 31, v6
	s_and_b64 s[42:43], s[14:15], exec
	v_lshl_add_u64 v[20:21], v[6:7], 1, v[4:5]
	s_cselect_b32 s42, 0, 0x8000
	s_mov_b32 s43, s36
	v_lshl_add_u64 v[22:23], v[20:21], 0, s[42:43]
	v_mov_b64_e32 v[4:5], v[240:241]
	v_mov_b64_e32 v[6:7], v[242:243]
	v_mov_b64_e32 v[8:9], v[236:237]
	v_mov_b64_e32 v[10:11], v[238:239]
	v_mov_b64_e32 v[12:13], v[224:225]
	v_mov_b64_e32 v[14:15], v[226:227]
	v_mov_b64_e32 v[132:133], v[220:221]
	v_mov_b64_e32 v[134:135], v[222:223]
	v_mov_b64_e32 v[136:137], v[232:233]
	v_mov_b64_e32 v[138:139], v[234:235]
	v_mov_b64_e32 v[140:141], v[228:229]
	v_mov_b64_e32 v[142:143], v[230:231]
	v_mov_b64_e32 v[144:145], v[216:217]
	v_mov_b64_e32 v[146:147], v[218:219]
	v_mov_b64_e32 v[148:149], v[212:213]
	v_mov_b64_e32 v[150:151], v[214:215]
	s_andn2_b64 vcc, exec, s[40:41]
	s_mov_b64 s[40:41], -1
	s_cbranch_vccnz .LBB0_539
	s_waitcnt vmcnt(0)
	s_mov_b64 s[40:41], 0

.LBB0_543:
	v_mov_b32_e32 v20, v18
	v_mov_b32_e32 v21, v18
	v_mov_b32_e32 v22, v18
	v_mov_b32_e32 v23, v18
	v_mov_b32_e32 v24, v18
	v_mov_b32_e32 v25, v18
	v_mov_b32_e32 v26, v18
	v_mov_b32_e32 v27, v18
	v_mov_b32_e32 v28, v18
	v_mov_b32_e32 v29, v18
	v_mov_b32_e32 v30, v18
	v_mov_b32_e32 v31, v18
	v_mov_b32_e32 v32, v18
	v_mov_b32_e32 v33, v18
	v_mov_b32_e32 v19, v18
	v_mov_b64_e32 v[34:35], v[32:33]
	v_mov_b64_e32 v[32:33], v[30:31]
	v_mov_b64_e32 v[30:31], v[28:29]
	v_mov_b64_e32 v[28:29], v[26:27]
	v_mov_b64_e32 v[26:27], v[24:25]
	v_mov_b64_e32 v[24:25], v[22:23]
	v_mov_b64_e32 v[22:23], v[20:21]
	v_mov_b64_e32 v[20:21], v[18:19]
	s_lshl_b32 s37, s13, 6
	s_and_b64 s[14:15], s[14:15], exec
	s_waitcnt lgkmcnt(11)
	v_mfma_f32_32x32x16_bf16 v[20:35], v[84:87], v[148:151], v[20:35]
	s_mul_i32 s13, s25, 0x410
	s_cselect_b32 s76, 0x400, s37
	s_add_i32 s75, s13, 0
	s_lshl_b32 s56, s38, 5
	v_or_b32_e32 v193, s76, v188
	s_add_i32 s75, s75, 0x20400
	s_addk_i32 s76, 0xff61
	s_waitcnt lgkmcnt(10)
	v_mfma_f32_32x32x16_bf16 v[20:35], v[48:51], v[144:147], v[20:35]
	s_add_i32 s56, s56, s72
	s_cmp_gt_i32 s56, s76
	s_cselect_b64 s[14:15], -1, 0
	v_add_u32_e32 v19, s56, v190
	s_and_b64 s[14:15], s[8:9], s[14:15]
	v_sub_u32_e32 v88, v193, v19
	s_andn2_b64 vcc, exec, s[14:15]
	s_waitcnt lgkmcnt(9)
	v_mfma_f32_32x32x16_bf16 v[20:35], v[44:47], v[132:135], v[20:35]
	s_waitcnt lgkmcnt(8)
	v_mfma_f32_32x32x16_bf16 v[20:35], v[40:43], v[12:15], v[20:35]
	s_cbranch_vccnz .LBB0_545
	v_add_u32_e32 v19, 0x80, v88
	v_med3_i32 v52, v19, 0, v185
	v_lshl_add_u32 v60, v52, 2, s75
	v_max_i32_e32 v52, 1, v19
	v_add_u32_e32 v52, -1, v52
	v_min_u32_e32 v52, 0x100, v52
	v_lshl_add_u32 v61, v52, 2, s75
	v_max_i32_e32 v52, 2, v19
	v_add_u32_e32 v52, -2, v52
	v_min_u32_e32 v52, 0x100, v52
	v_lshl_add_u32 v62, v52, 2, s75
	v_max_i32_e32 v52, 3, v19
	v_add_u32_e32 v52, -3, v52
	v_min_u32_e32 v52, 0x100, v52
	v_lshl_add_u32 v63, v52, 2, s75
	v_max_i32_e32 v52, 8, v19
	v_add_u32_e32 v52, -8, v52
	v_min_u32_e32 v52, 0x100, v52
	v_lshl_add_u32 v64, v52, 2, s75
	v_max_i32_e32 v52, 9, v19
	v_add_u32_e32 v52, -9, v52
	v_min_u32_e32 v52, 0x100, v52
	v_lshl_add_u32 v65, v52, 2, s75
	v_max_i32_e32 v52, 10, v19
	v_add_u32_e32 v52, -10, v52
	v_min_u32_e32 v52, 0x100, v52
	v_lshl_add_u32 v66, v52, 2, s75
	v_max_i32_e32 v52, 11, v19
	v_add_u32_e32 v52, -11, v52
	v_min_u32_e32 v52, 0x100, v52
	v_lshl_add_u32 v67, v52, 2, s75
	v_max_i32_e32 v52, 16, v19
	v_max_i32_e32 v53, 17, v19
	v_max_i32_e32 v54, 18, v19
	v_max_i32_e32 v55, 19, v19
	v_max_i32_e32 v56, 24, v19
	v_max_i32_e32 v57, 25, v19
	v_max_i32_e32 v58, 26, v19
	v_add_u32_e32 v52, -16, v52
	v_subrev_u32_e32 v53, 17, v53
	v_subrev_u32_e32 v54, 18, v54
	v_subrev_u32_e32 v55, 19, v55
	v_subrev_u32_e32 v56, 24, v56
	v_subrev_u32_e32 v57, 25, v57
	v_subrev_u32_e32 v58, 26, v58
	v_max_i32_e32 v19, 27, v19
	v_min_u32_e32 v52, 0x100, v52
	v_min_u32_e32 v53, 0x100, v53
	v_min_u32_e32 v54, 0x100, v54
	v_min_u32_e32 v55, 0x100, v55
	v_min_u32_e32 v56, 0x100, v56
	v_min_u32_e32 v57, 0x100, v57
	v_min_u32_e32 v58, 0x100, v58
	v_subrev_u32_e32 v19, 27, v19
	v_lshl_add_u32 v52, v52, 2, s75
	v_lshl_add_u32 v53, v53, 2, s75
	v_lshl_add_u32 v54, v54, 2, s75
	v_lshl_add_u32 v55, v55, 2, s75
	v_lshl_add_u32 v56, v56, 2, s75
	v_lshl_add_u32 v57, v57, 2, s75
	v_lshl_add_u32 v58, v58, 2, s75
	v_min_u32_e32 v19, 0x100, v19
	v_lshl_add_u32 v19, v19, 2, s75
	ds_read_b32 v52, v52
	ds_read_b32 v53, v53
	ds_read_b32 v54, v54
	ds_read_b32 v55, v55
	ds_read_b32 v56, v56
	ds_read_b32 v57, v57
	ds_read_b32 v58, v58
	ds_read_b32 v59, v19
	ds_read_b32 v60, v60
	ds_read_b32 v61, v61
	ds_read_b32 v62, v62
	ds_read_b32 v63, v63
	ds_read_b32 v64, v64
	ds_read_b32 v65, v65
	ds_read_b32 v66, v66
	ds_read_b32 v67, v67
	s_waitcnt lgkmcnt(8)
	v_pk_add_f32 v[34:35], v[34:35], v[58:59]
	v_pk_add_f32 v[32:33], v[32:33], v[56:57]
	v_pk_add_f32 v[30:31], v[30:31], v[54:55]
	v_pk_add_f32 v[28:29], v[28:29], v[52:53]
	s_waitcnt lgkmcnt(0)
	v_pk_add_f32 v[26:27], v[26:27], v[66:67]
	v_pk_add_f32 v[24:25], v[24:25], v[64:65]
	v_pk_add_f32 v[22:23], v[22:23], v[62:63]
	v_pk_add_f32 v[20:21], v[20:21], v[60:61]
